# merge chain epilogue: one extra dword load per lane touches the gate tile needed two branches later (L2 warm-up), counted waits +1 (on top of v20)
# baseline (speedup 1.0000x reference)
; __device__ __forceinline__ float rcpf(float x) { return __builtin_amdgcn_rcpf(x); }
;     __device__ __forceinline__ bool chain(f32x4 (&acc)[2][2][4][2], const Unit& u, int wr, int wc, int fr, int fq) const {
;         const int row0 = u.pm * BM + wr * 64 + fr; const int bi = u.pn >> 2, nn = u.pn & 3; const bool lastb = bi == 3;
; #pragma unroll
;         for (int ai = 0; ai < 2; ++ai)
; #pragma unroll
;             for (int mp = 0; mp < 2; ++mp) { u32x2 g0[2][2], g1[2][2];
; #pragma unroll
;                 for (int mm = 0; mm < 2; ++mm)
; #pragma unroll
;                     for (int bj = 0; bj < 2; ++bj) { const size_t row = (size_t)(row0 + ai * HALF + (mp * 2 + mm) * 16); const int c0 = nn * BM + bj * HALF + wc * 32 + 8 * fq;
;                         g0[mm][bj] = *(const u32x2*)(gates + row * 4096 + bi * 1024 + c0);
;                         g1[mm][bj] = lastb ? g0[mm][bj] : *(const u32x2*)(gates + row * 4096 + (bi + 1) * 1024 + c0); }
; #pragma unroll
;                 for (int mm = 0; mm < 2; ++mm)
; #pragma unroll
;                     for (int bj = 0; bj < 2; ++bj) { const int m = mp * 2 + mm; const size_t row = (size_t)(row0 + ai * HALF + m * 16); const int c0 = nn * BM + bj * HALF + wc * 32 + 8 * fq; float ga[8], gb[8], o[8];
;                         unpack_u8x8(g0[mm][bj], ga); unpack_u8x8(g1[mm][bj], gb);
; #pragma unroll
;                         for (int n = 0; n < 2; ++n)
; #pragma unroll
;                             for (int j = 0; j < 4; ++j) { const float f = lastb ? ga[n * 4 + j] * (1.f / 255.f) : ga[n * 4 + j] * rcpf(gb[n * 4 + j]); const float v = acc[ai][bj][m][n][j] * f; acc[ai][bj][m][n][j] = v; o[n * 4 + j] = v; }
.LBB0_2011:
	s_ashr_i32 s24, s30, 2
	s_lshl_b32 s25, s30, 8
	s_and_b32 s25, s25, 0x300
	s_mov_b64 s[64:65], s[66:67]
	v_readlane_b32 s28, v251, 34
	v_readlane_b32 s29, v251, 35
	v_lshl_add_u32 v142, s2, 8, v168
	s_lshl_b32 s31, s24, 10
	s_add_i32 s31, s31, s25
	v_lshlrev_b32_e32 v143, 11, v142
	v_lshlrev_b32_e32 v142, 12, v142
	v_add_u32_e32 v142, v142, v170
	s_add_u32 s28, s28, s31
	s_addc_u32 s29, s29, 0
	s_cmp_eq_u32 s24, 3
	s_cselect_b64 s[38:39], 0, -1
	s_cbranch_scc1 .Lmy_mg_last
	global_load_dwordx2 v[144:145], v142, s[28:29]
	global_load_dwordx2 v[146:147], v142, s[28:29] offset:128
	global_load_dwordx2 v[148:149], v142, s[28:29] offset:1024
	global_load_dwordx2 v[150:151], v142, s[28:29] offset:1152
	v_add_u32_e32 v142, 0x10000, v142
	global_load_dwordx2 v[152:153], v142, s[28:29]
	global_load_dwordx2 v[154:155], v142, s[28:29] offset:128
	global_load_dwordx2 v[156:157], v142, s[28:29] offset:1024
	global_load_dwordx2 v[158:159], v142, s[28:29] offset:1152
	v_add_u32_e32 v142, 0x10000, v142
	global_load_dwordx2 v[160:161], v142, s[28:29]
	global_load_dwordx2 v[162:163], v142, s[28:29] offset:128
	global_load_dwordx2 v[164:165], v142, s[28:29] offset:1024
	global_load_dwordx2 v[166:167], v142, s[28:29] offset:1152
	v_add_u32_e32 v142, 0x10000, v142
	global_load_dwordx2 v[172:173], v142, s[28:29]
	global_load_dwordx2 v[174:175], v142, s[28:29] offset:128
	global_load_dwordx2 v[176:177], v142, s[28:29] offset:1024
	global_load_dwordx2 v[178:179], v142, s[28:29] offset:1152
	v_add_u32_e32 v142, 0x50000, v142
	global_load_dwordx2 v[180:181], v142, s[28:29]
	global_load_dwordx2 v[182:183], v142, s[28:29] offset:128
	global_load_dwordx2 v[198:199], v142, s[28:29] offset:1024
	global_load_dwordx2 v[200:201], v142, s[28:29] offset:1152
	v_add_u32_e32 v142, 0x10000, v142
	global_load_dwordx2 v[202:203], v142, s[28:29]
	global_load_dwordx2 v[204:205], v142, s[28:29] offset:128
	global_load_dwordx2 v[206:207], v142, s[28:29] offset:1024
	global_load_dwordx2 v[208:209], v142, s[28:29] offset:1152
	v_add_u32_e32 v142, 0x10000, v142
	global_load_dwordx2 v[210:211], v142, s[28:29]
	global_load_dwordx2 v[212:213], v142, s[28:29] offset:128
	global_load_dwordx2 v[214:215], v142, s[28:29] offset:1024
	global_load_dwordx2 v[220:221], v142, s[28:29] offset:1152
	v_add_u32_e32 v142, 0x10000, v142
	global_load_dwordx2 v[222:223], v142, s[28:29]
	global_load_dwordx2 v[224:225], v142, s[28:29] offset:128
	global_load_dwordx2 v[226:227], v142, s[28:29] offset:1024
	global_load_dwordx2 v[228:229], v142, s[28:29] offset:1152
	s_cmp_lt_u32 s24, 2
	s_cselect_b32 s31, 0x800, 0
	s_add_u32 s40, s28, s31
	s_addc_u32 s41, s29, 0
	v_lshrrev_b32_e32 v230, 1, v216
	v_and_b32_e32 v0, 1, v216
	v_lshl_add_u32 v230, s2, 8, v230
	v_lshlrev_b32_e32 v230, 12, v230
	v_lshl_or_b32 v230, v0, 7, v230
	global_load_dword v0, v230, s[40:41]
	s_waitcnt vmcnt(29)
	v_cvt_f32_ubyte0_e32 v230, v144
	v_cvt_f32_ubyte1_e32 v231, v144
	v_cvt_f32_ubyte2_e32 v232, v144
	v_cvt_f32_ubyte3_e32 v233, v144
	v_cvt_f32_ubyte0_e32 v242, v148
	v_cvt_f32_ubyte1_e32 v243, v148
	v_cvt_f32_ubyte2_e32 v248, v148
	v_cvt_f32_ubyte3_e32 v249, v148
	v_rcp_iflag_f32_e32 v242, v242
	v_rcp_iflag_f32_e32 v243, v243
	v_rcp_iflag_f32_e32 v248, v248
	v_rcp_iflag_f32_e32 v249, v249
	v_mul_f32_e32 v230, v242, v230
	v_mul_f32_e32 v231, v243, v231
	v_mul_f32_e32 v232, v248, v232
	v_mul_f32_e32 v233, v249, v233
	v_mul_f32_e32 v126, v126, v230
	v_mul_f32_e32 v127, v127, v231
	v_mul_f32_e32 v128, v128, v232
	v_mul_f32_e32 v129, v129, v233
	v_cvt_f32_ubyte0_e32 v230, v145
	v_cvt_f32_ubyte1_e32 v231, v145
	v_cvt_f32_ubyte2_e32 v232, v145
	v_cvt_f32_ubyte3_e32 v233, v145
	v_cvt_f32_ubyte0_e32 v242, v149
	v_cvt_f32_ubyte1_e32 v243, v149
	v_cvt_f32_ubyte2_e32 v248, v149
	v_cvt_f32_ubyte3_e32 v249, v149
	v_rcp_iflag_f32_e32 v242, v242
	v_rcp_iflag_f32_e32 v243, v243
	v_rcp_iflag_f32_e32 v248, v248
	v_rcp_iflag_f32_e32 v249, v249
	v_mul_f32_e32 v230, v242, v230
	v_mul_f32_e32 v231, v243, v231
	v_mul_f32_e32 v232, v248, v232
	v_mul_f32_e32 v233, v249, v233
	v_mul_f32_e32 v122, v122, v230
	v_mul_f32_e32 v123, v123, v231
	v_mul_f32_e32 v124, v124, v232
	v_mul_f32_e32 v125, v125, v233
	v_cvt_f32_ubyte0_e32 v230, v146
	v_cvt_f32_ubyte1_e32 v231, v146
	v_cvt_f32_ubyte2_e32 v232, v146
	v_cvt_f32_ubyte3_e32 v233, v146
	v_cvt_f32_ubyte0_e32 v242, v150
	v_cvt_f32_ubyte1_e32 v243, v150
	v_cvt_f32_ubyte2_e32 v248, v150
	v_cvt_f32_ubyte3_e32 v249, v150
	v_rcp_iflag_f32_e32 v242, v242
	v_rcp_iflag_f32_e32 v243, v243
	v_rcp_iflag_f32_e32 v248, v248
	v_rcp_iflag_f32_e32 v249, v249
	v_mul_f32_e32 v230, v242, v230
	v_mul_f32_e32 v231, v243, v231
	v_mul_f32_e32 v232, v248, v232
	v_mul_f32_e32 v233, v249, v233
	v_mul_f32_e32 v94, v94, v230
	v_mul_f32_e32 v95, v95, v231
	v_mul_f32_e32 v96, v96, v232
	v_mul_f32_e32 v97, v97, v233
	v_cvt_f32_ubyte0_e32 v230, v147
	v_cvt_f32_ubyte1_e32 v231, v147
	v_cvt_f32_ubyte2_e32 v232, v147
	v_cvt_f32_ubyte3_e32 v233, v147
	v_cvt_f32_ubyte0_e32 v242, v151
	v_cvt_f32_ubyte1_e32 v243, v151
	v_cvt_f32_ubyte2_e32 v248, v151
	v_cvt_f32_ubyte3_e32 v249, v151
	v_rcp_iflag_f32_e32 v242, v242
	v_rcp_iflag_f32_e32 v243, v243
	v_rcp_iflag_f32_e32 v248, v248
	v_rcp_iflag_f32_e32 v249, v249
	v_mul_f32_e32 v230, v242, v230
	v_mul_f32_e32 v231, v243, v231
	v_mul_f32_e32 v232, v248, v232
	v_mul_f32_e32 v233, v249, v233
	v_mul_f32_e32 v90, v90, v230
	v_mul_f32_e32 v91, v91, v231
	v_mul_f32_e32 v92, v92, v232
	v_mul_f32_e32 v93, v93, v233
	s_waitcnt vmcnt(25)
; __device__ __forceinline__ float rcpf(float x) { return __builtin_amdgcn_rcpf(x); }
;     __device__ __forceinline__ bool chain(f32x4 (&acc)[2][2][4][2], const Unit& u, int wr, int wc, int fr, int fq) const {
;     ...
;                 for (int mm = 0; mm < 2; ++mm)
; #pragma unroll
;                     for (int bj = 0; bj < 2; ++bj) { const int m = mp * 2 + mm; const size_t row = (size_t)(row0 + ai * HALF + m * 16); const int c0 = nn * BM + bj * HALF + wc * 32 + 8 * fq; float ga[8], gb[8], o[8];
;                         unpack_u8x8(g0[mm][bj], ga); unpack_u8x8(g1[mm][bj], gb);
; #pragma unroll
;                         for (int n = 0; n < 2; ++n)
; #pragma unroll
;                             for (int j = 0; j < 4; ++j) { const float f = lastb ? ga[n * 4 + j] * (1.f / 255.f) : ga[n * 4 + j] * rcpf(gb[n * 4 + j]); const float v = acc[ai][bj][m][n][j] * f; acc[ai][bj][m][n][j] = v; o[n * 4 + j] = v; }
	v_cvt_f32_ubyte0_e32 v230, v152
	v_cvt_f32_ubyte1_e32 v231, v152
	v_cvt_f32_ubyte2_e32 v232, v152
	v_cvt_f32_ubyte3_e32 v233, v152
	v_cvt_f32_ubyte0_e32 v242, v156
	v_cvt_f32_ubyte1_e32 v243, v156
	v_cvt_f32_ubyte2_e32 v248, v156
	v_cvt_f32_ubyte3_e32 v249, v156
	v_rcp_iflag_f32_e32 v242, v242
	v_rcp_iflag_f32_e32 v243, v243
	v_rcp_iflag_f32_e32 v248, v248
	v_rcp_iflag_f32_e32 v249, v249
	v_mul_f32_e32 v230, v242, v230
	v_mul_f32_e32 v231, v243, v231
	v_mul_f32_e32 v232, v248, v232
	v_mul_f32_e32 v233, v249, v233
	v_mul_f32_e32 v118, v118, v230
	v_mul_f32_e32 v119, v119, v231
	v_mul_f32_e32 v120, v120, v232
	v_mul_f32_e32 v121, v121, v233
	v_cvt_f32_ubyte0_e32 v230, v153
	v_cvt_f32_ubyte1_e32 v231, v153
	v_cvt_f32_ubyte2_e32 v232, v153
	v_cvt_f32_ubyte3_e32 v233, v153
	v_cvt_f32_ubyte0_e32 v242, v157
	v_cvt_f32_ubyte1_e32 v243, v157
	v_cvt_f32_ubyte2_e32 v248, v157
	v_cvt_f32_ubyte3_e32 v249, v157
	v_rcp_iflag_f32_e32 v242, v242
	v_rcp_iflag_f32_e32 v243, v243
	v_rcp_iflag_f32_e32 v248, v248
	v_rcp_iflag_f32_e32 v249, v249
	v_mul_f32_e32 v230, v242, v230
	v_mul_f32_e32 v231, v243, v231
	v_mul_f32_e32 v232, v248, v232
	v_mul_f32_e32 v233, v249, v233
	v_mul_f32_e32 v114, v114, v230
	v_mul_f32_e32 v115, v115, v231
	v_mul_f32_e32 v116, v116, v232
	v_mul_f32_e32 v117, v117, v233
	v_cvt_f32_ubyte0_e32 v230, v154
	v_cvt_f32_ubyte1_e32 v231, v154
	v_cvt_f32_ubyte2_e32 v232, v154
	v_cvt_f32_ubyte3_e32 v233, v154
	v_cvt_f32_ubyte0_e32 v242, v158
	v_cvt_f32_ubyte1_e32 v243, v158
	v_cvt_f32_ubyte2_e32 v248, v158
	v_cvt_f32_ubyte3_e32 v249, v158
	v_rcp_iflag_f32_e32 v242, v242
	v_rcp_iflag_f32_e32 v243, v243
	v_rcp_iflag_f32_e32 v248, v248
	v_rcp_iflag_f32_e32 v249, v249
	v_mul_f32_e32 v230, v242, v230
	v_mul_f32_e32 v231, v243, v231
	v_mul_f32_e32 v232, v248, v232
	v_mul_f32_e32 v233, v249, v233
	v_mul_f32_e32 v86, v86, v230
	v_mul_f32_e32 v87, v87, v231
	v_mul_f32_e32 v88, v88, v232
	v_mul_f32_e32 v89, v89, v233
	v_cvt_f32_ubyte0_e32 v230, v155
	v_cvt_f32_ubyte1_e32 v231, v155
	v_cvt_f32_ubyte2_e32 v232, v155
	v_cvt_f32_ubyte3_e32 v233, v155
	v_cvt_f32_ubyte0_e32 v242, v159
	v_cvt_f32_ubyte1_e32 v243, v159
	v_cvt_f32_ubyte2_e32 v248, v159
	v_cvt_f32_ubyte3_e32 v249, v159
	v_rcp_iflag_f32_e32 v242, v242
	v_rcp_iflag_f32_e32 v243, v243
	v_rcp_iflag_f32_e32 v248, v248
	v_rcp_iflag_f32_e32 v249, v249
	v_mul_f32_e32 v230, v242, v230
	v_mul_f32_e32 v231, v243, v231
	v_mul_f32_e32 v232, v248, v232
	v_mul_f32_e32 v233, v249, v233
	v_mul_f32_e32 v82, v82, v230
	v_mul_f32_e32 v83, v83, v231
	v_mul_f32_e32 v84, v84, v232
	v_mul_f32_e32 v85, v85, v233
	s_waitcnt vmcnt(21)
	v_cvt_f32_ubyte0_e32 v230, v160
	v_cvt_f32_ubyte1_e32 v231, v160
	v_cvt_f32_ubyte2_e32 v232, v160
	v_cvt_f32_ubyte3_e32 v233, v160
	v_cvt_f32_ubyte0_e32 v242, v164
	v_cvt_f32_ubyte1_e32 v243, v164
	v_cvt_f32_ubyte2_e32 v248, v164
	v_cvt_f32_ubyte3_e32 v249, v164
	v_rcp_iflag_f32_e32 v242, v242
	v_rcp_iflag_f32_e32 v243, v243
	v_rcp_iflag_f32_e32 v248, v248
	v_rcp_iflag_f32_e32 v249, v249
	v_mul_f32_e32 v230, v242, v230
	v_mul_f32_e32 v231, v243, v231
	v_mul_f32_e32 v232, v248, v232
	v_mul_f32_e32 v233, v249, v233
	v_mul_f32_e32 v110, v110, v230
	v_mul_f32_e32 v111, v111, v231
	v_mul_f32_e32 v112, v112, v232
	v_mul_f32_e32 v113, v113, v233
	v_cvt_f32_ubyte0_e32 v230, v161
	v_cvt_f32_ubyte1_e32 v231, v161
	v_cvt_f32_ubyte2_e32 v232, v161
	v_cvt_f32_ubyte3_e32 v233, v161
	v_cvt_f32_ubyte0_e32 v242, v165
	v_cvt_f32_ubyte1_e32 v243, v165
	v_cvt_f32_ubyte2_e32 v248, v165
	v_cvt_f32_ubyte3_e32 v249, v165
	v_rcp_iflag_f32_e32 v242, v242
	v_rcp_iflag_f32_e32 v243, v243
	v_rcp_iflag_f32_e32 v248, v248
	v_rcp_iflag_f32_e32 v249, v249
	v_mul_f32_e32 v230, v242, v230
	v_mul_f32_e32 v231, v243, v231
	v_mul_f32_e32 v232, v248, v232
	v_mul_f32_e32 v233, v249, v233
	v_mul_f32_e32 v106, v106, v230
	v_mul_f32_e32 v107, v107, v231
	v_mul_f32_e32 v108, v108, v232
	v_mul_f32_e32 v109, v109, v233
	v_cvt_f32_ubyte0_e32 v230, v162
	v_cvt_f32_ubyte1_e32 v231, v162
	v_cvt_f32_ubyte2_e32 v232, v162
	v_cvt_f32_ubyte3_e32 v233, v162
	v_cvt_f32_ubyte0_e32 v242, v166
	v_cvt_f32_ubyte1_e32 v243, v166
	v_cvt_f32_ubyte2_e32 v248, v166
	v_cvt_f32_ubyte3_e32 v249, v166
	v_rcp_iflag_f32_e32 v242, v242
	v_rcp_iflag_f32_e32 v243, v243
	v_rcp_iflag_f32_e32 v248, v248
	v_rcp_iflag_f32_e32 v249, v249
	v_mul_f32_e32 v230, v242, v230
	v_mul_f32_e32 v231, v243, v231
	v_mul_f32_e32 v232, v248, v232
	v_mul_f32_e32 v233, v249, v233
	v_mul_f32_e32 v78, v78, v230
	v_mul_f32_e32 v79, v79, v231
	v_mul_f32_e32 v80, v80, v232
	v_mul_f32_e32 v81, v81, v233
	v_cvt_f32_ubyte0_e32 v230, v163
	v_cvt_f32_ubyte1_e32 v231, v163
	v_cvt_f32_ubyte2_e32 v232, v163
	v_cvt_f32_ubyte3_e32 v233, v163
	v_cvt_f32_ubyte0_e32 v242, v167
	v_cvt_f32_ubyte1_e32 v243, v167
	v_cvt_f32_ubyte2_e32 v248, v167
	v_cvt_f32_ubyte3_e32 v249, v167
	v_rcp_iflag_f32_e32 v242, v242
	v_rcp_iflag_f32_e32 v243, v243
	v_rcp_iflag_f32_e32 v248, v248
	v_rcp_iflag_f32_e32 v249, v249
	v_mul_f32_e32 v230, v242, v230
	v_mul_f32_e32 v231, v243, v231
	v_mul_f32_e32 v232, v248, v232
	v_mul_f32_e32 v233, v249, v233
	v_mul_f32_e32 v74, v74, v230
	v_mul_f32_e32 v75, v75, v231
	v_mul_f32_e32 v76, v76, v232
	v_mul_f32_e32 v77, v77, v233
	s_waitcnt vmcnt(17)
; __device__ __forceinline__ float rcpf(float x) { return __builtin_amdgcn_rcpf(x); }
;     __device__ __forceinline__ bool chain(f32x4 (&acc)[2][2][4][2], const Unit& u, int wr, int wc, int fr, int fq) const {
;     ...
;                 for (int mm = 0; mm < 2; ++mm)
; #pragma unroll
;                     for (int bj = 0; bj < 2; ++bj) { const int m = mp * 2 + mm; const size_t row = (size_t)(row0 + ai * HALF + m * 16); const int c0 = nn * BM + bj * HALF + wc * 32 + 8 * fq; float ga[8], gb[8], o[8];
;                         unpack_u8x8(g0[mm][bj], ga); unpack_u8x8(g1[mm][bj], gb);
; #pragma unroll
;                         for (int n = 0; n < 2; ++n)
; #pragma unroll
;                             for (int j = 0; j < 4; ++j) { const float f = lastb ? ga[n * 4 + j] * (1.f / 255.f) : ga[n * 4 + j] * rcpf(gb[n * 4 + j]); const float v = acc[ai][bj][m][n][j] * f; acc[ai][bj][m][n][j] = v; o[n * 4 + j] = v; }
	v_cvt_f32_ubyte0_e32 v230, v172
	v_cvt_f32_ubyte1_e32 v231, v172
	v_cvt_f32_ubyte2_e32 v232, v172
	v_cvt_f32_ubyte3_e32 v233, v172
	v_cvt_f32_ubyte0_e32 v242, v176
	v_cvt_f32_ubyte1_e32 v243, v176
	v_cvt_f32_ubyte2_e32 v248, v176
	v_cvt_f32_ubyte3_e32 v249, v176
	v_rcp_iflag_f32_e32 v242, v242
	v_rcp_iflag_f32_e32 v243, v243
	v_rcp_iflag_f32_e32 v248, v248
	v_rcp_iflag_f32_e32 v249, v249
	v_mul_f32_e32 v230, v242, v230
	v_mul_f32_e32 v231, v243, v231
	v_mul_f32_e32 v232, v248, v232
	v_mul_f32_e32 v233, v249, v233
	v_mul_f32_e32 v102, v102, v230
	v_mul_f32_e32 v103, v103, v231
	v_mul_f32_e32 v104, v104, v232
	v_mul_f32_e32 v105, v105, v233
	v_cvt_f32_ubyte0_e32 v230, v173
	v_cvt_f32_ubyte1_e32 v231, v173
	v_cvt_f32_ubyte2_e32 v232, v173
	v_cvt_f32_ubyte3_e32 v233, v173
	v_cvt_f32_ubyte0_e32 v242, v177
	v_cvt_f32_ubyte1_e32 v243, v177
	v_cvt_f32_ubyte2_e32 v248, v177
	v_cvt_f32_ubyte3_e32 v249, v177
	v_rcp_iflag_f32_e32 v242, v242
	v_rcp_iflag_f32_e32 v243, v243
	v_rcp_iflag_f32_e32 v248, v248
	v_rcp_iflag_f32_e32 v249, v249
	v_mul_f32_e32 v230, v242, v230
	v_mul_f32_e32 v231, v243, v231
	v_mul_f32_e32 v232, v248, v232
	v_mul_f32_e32 v233, v249, v233
	v_mul_f32_e32 v98, v98, v230
	v_mul_f32_e32 v99, v99, v231
	v_mul_f32_e32 v100, v100, v232
	v_mul_f32_e32 v101, v101, v233
	v_cvt_f32_ubyte0_e32 v230, v174
	v_cvt_f32_ubyte1_e32 v231, v174
	v_cvt_f32_ubyte2_e32 v232, v174
	v_cvt_f32_ubyte3_e32 v233, v174
	v_cvt_f32_ubyte0_e32 v242, v178
	v_cvt_f32_ubyte1_e32 v243, v178
	v_cvt_f32_ubyte2_e32 v248, v178
	v_cvt_f32_ubyte3_e32 v249, v178
	v_rcp_iflag_f32_e32 v242, v242
	v_rcp_iflag_f32_e32 v243, v243
	v_rcp_iflag_f32_e32 v248, v248
	v_rcp_iflag_f32_e32 v249, v249
	v_mul_f32_e32 v230, v242, v230
	v_mul_f32_e32 v231, v243, v231
	v_mul_f32_e32 v232, v248, v232
	v_mul_f32_e32 v233, v249, v233
	v_mul_f32_e32 v70, v70, v230
	v_mul_f32_e32 v71, v71, v231
	v_mul_f32_e32 v72, v72, v232
	v_mul_f32_e32 v73, v73, v233
	v_cvt_f32_ubyte0_e32 v230, v175
	v_cvt_f32_ubyte1_e32 v231, v175
	v_cvt_f32_ubyte2_e32 v232, v175
	v_cvt_f32_ubyte3_e32 v233, v175
	v_cvt_f32_ubyte0_e32 v242, v179
	v_cvt_f32_ubyte1_e32 v243, v179
	v_cvt_f32_ubyte2_e32 v248, v179
	v_cvt_f32_ubyte3_e32 v249, v179
	v_rcp_iflag_f32_e32 v242, v242
	v_rcp_iflag_f32_e32 v243, v243
	v_rcp_iflag_f32_e32 v248, v248
	v_rcp_iflag_f32_e32 v249, v249
	v_mul_f32_e32 v230, v242, v230
	v_mul_f32_e32 v231, v243, v231
	v_mul_f32_e32 v232, v248, v232
	v_mul_f32_e32 v233, v249, v233
	v_mul_f32_e32 v66, v66, v230
	v_mul_f32_e32 v67, v67, v231
	v_mul_f32_e32 v68, v68, v232
	v_mul_f32_e32 v69, v69, v233
	s_waitcnt vmcnt(13)
	v_cvt_f32_ubyte0_e32 v230, v180
	v_cvt_f32_ubyte1_e32 v231, v180
	v_cvt_f32_ubyte2_e32 v232, v180
	v_cvt_f32_ubyte3_e32 v233, v180
	v_cvt_f32_ubyte0_e32 v242, v198
	v_cvt_f32_ubyte1_e32 v243, v198
	v_cvt_f32_ubyte2_e32 v248, v198
	v_cvt_f32_ubyte3_e32 v249, v198
	v_rcp_iflag_f32_e32 v242, v242
	v_rcp_iflag_f32_e32 v243, v243
	v_rcp_iflag_f32_e32 v248, v248
	v_rcp_iflag_f32_e32 v249, v249
	v_mul_f32_e32 v230, v242, v230
	v_mul_f32_e32 v231, v243, v231
	v_mul_f32_e32 v232, v248, v232
	v_mul_f32_e32 v233, v249, v233
	v_mul_f32_e32 v62, v62, v230
	v_mul_f32_e32 v63, v63, v231
	v_mul_f32_e32 v64, v64, v232
	v_mul_f32_e32 v65, v65, v233
	v_cvt_f32_ubyte0_e32 v230, v181
	v_cvt_f32_ubyte1_e32 v231, v181
	v_cvt_f32_ubyte2_e32 v232, v181
	v_cvt_f32_ubyte3_e32 v233, v181
	v_cvt_f32_ubyte0_e32 v242, v199
	v_cvt_f32_ubyte1_e32 v243, v199
	v_cvt_f32_ubyte2_e32 v248, v199
	v_cvt_f32_ubyte3_e32 v249, v199
	v_rcp_iflag_f32_e32 v242, v242
	v_rcp_iflag_f32_e32 v243, v243
	v_rcp_iflag_f32_e32 v248, v248
	v_rcp_iflag_f32_e32 v249, v249
	v_mul_f32_e32 v230, v242, v230
	v_mul_f32_e32 v231, v243, v231
	v_mul_f32_e32 v232, v248, v232
	v_mul_f32_e32 v233, v249, v233
	v_mul_f32_e32 v58, v58, v230
	v_mul_f32_e32 v59, v59, v231
	v_mul_f32_e32 v60, v60, v232
	v_mul_f32_e32 v61, v61, v233
	v_cvt_f32_ubyte0_e32 v230, v182
	v_cvt_f32_ubyte1_e32 v231, v182
	v_cvt_f32_ubyte2_e32 v232, v182
	v_cvt_f32_ubyte3_e32 v233, v182
	v_cvt_f32_ubyte0_e32 v242, v200
	v_cvt_f32_ubyte1_e32 v243, v200
	v_cvt_f32_ubyte2_e32 v248, v200
	v_cvt_f32_ubyte3_e32 v249, v200
	v_rcp_iflag_f32_e32 v242, v242
	v_rcp_iflag_f32_e32 v243, v243
	v_rcp_iflag_f32_e32 v248, v248
	v_rcp_iflag_f32_e32 v249, v249
	v_mul_f32_e32 v230, v242, v230
	v_mul_f32_e32 v231, v243, v231
	v_mul_f32_e32 v232, v248, v232
	v_mul_f32_e32 v233, v249, v233
	v_mul_f32_e32 v30, v30, v230
	v_mul_f32_e32 v31, v31, v231
	v_mul_f32_e32 v32, v32, v232
	v_mul_f32_e32 v33, v33, v233
	v_cvt_f32_ubyte0_e32 v230, v183
	v_cvt_f32_ubyte1_e32 v231, v183
	v_cvt_f32_ubyte2_e32 v232, v183
	v_cvt_f32_ubyte3_e32 v233, v183
	v_cvt_f32_ubyte0_e32 v242, v201
	v_cvt_f32_ubyte1_e32 v243, v201
	v_cvt_f32_ubyte2_e32 v248, v201
	v_cvt_f32_ubyte3_e32 v249, v201
	v_rcp_iflag_f32_e32 v242, v242
	v_rcp_iflag_f32_e32 v243, v243
	v_rcp_iflag_f32_e32 v248, v248
	v_rcp_iflag_f32_e32 v249, v249
	v_mul_f32_e32 v230, v242, v230
	v_mul_f32_e32 v231, v243, v231
	v_mul_f32_e32 v232, v248, v232
	v_mul_f32_e32 v233, v249, v233
	v_mul_f32_e32 v26, v26, v230
	v_mul_f32_e32 v27, v27, v231
	v_mul_f32_e32 v28, v28, v232
	v_mul_f32_e32 v29, v29, v233
	s_waitcnt vmcnt(9)
; __device__ __forceinline__ float rcpf(float x) { return __builtin_amdgcn_rcpf(x); }
;     __device__ __forceinline__ bool chain(f32x4 (&acc)[2][2][4][2], const Unit& u, int wr, int wc, int fr, int fq) const {
;     ...
;                 for (int mm = 0; mm < 2; ++mm)
; #pragma unroll
;                     for (int bj = 0; bj < 2; ++bj) { const int m = mp * 2 + mm; const size_t row = (size_t)(row0 + ai * HALF + m * 16); const int c0 = nn * BM + bj * HALF + wc * 32 + 8 * fq; float ga[8], gb[8], o[8];
;                         unpack_u8x8(g0[mm][bj], ga); unpack_u8x8(g1[mm][bj], gb);
; #pragma unroll
;                         for (int n = 0; n < 2; ++n)
; #pragma unroll
;                             for (int j = 0; j < 4; ++j) { const float f = lastb ? ga[n * 4 + j] * (1.f / 255.f) : ga[n * 4 + j] * rcpf(gb[n * 4 + j]); const float v = acc[ai][bj][m][n][j] * f; acc[ai][bj][m][n][j] = v; o[n * 4 + j] = v; }
	v_cvt_f32_ubyte0_e32 v230, v202
	v_cvt_f32_ubyte1_e32 v231, v202
	v_cvt_f32_ubyte2_e32 v232, v202
	v_cvt_f32_ubyte3_e32 v233, v202
	v_cvt_f32_ubyte0_e32 v242, v206
	v_cvt_f32_ubyte1_e32 v243, v206
	v_cvt_f32_ubyte2_e32 v248, v206
	v_cvt_f32_ubyte3_e32 v249, v206
	v_rcp_iflag_f32_e32 v242, v242
	v_rcp_iflag_f32_e32 v243, v243
	v_rcp_iflag_f32_e32 v248, v248
	v_rcp_iflag_f32_e32 v249, v249
	v_mul_f32_e32 v230, v242, v230
	v_mul_f32_e32 v231, v243, v231
	v_mul_f32_e32 v232, v248, v232
	v_mul_f32_e32 v233, v249, v233
	v_mul_f32_e32 v54, v54, v230
	v_mul_f32_e32 v55, v55, v231
	v_mul_f32_e32 v56, v56, v232
	v_mul_f32_e32 v57, v57, v233
	v_cvt_f32_ubyte0_e32 v230, v203
	v_cvt_f32_ubyte1_e32 v231, v203
	v_cvt_f32_ubyte2_e32 v232, v203
	v_cvt_f32_ubyte3_e32 v233, v203
	v_cvt_f32_ubyte0_e32 v242, v207
	v_cvt_f32_ubyte1_e32 v243, v207
	v_cvt_f32_ubyte2_e32 v248, v207
	v_cvt_f32_ubyte3_e32 v249, v207
	v_rcp_iflag_f32_e32 v242, v242
	v_rcp_iflag_f32_e32 v243, v243
	v_rcp_iflag_f32_e32 v248, v248
	v_rcp_iflag_f32_e32 v249, v249
	v_mul_f32_e32 v230, v242, v230
	v_mul_f32_e32 v231, v243, v231
	v_mul_f32_e32 v232, v248, v232
	v_mul_f32_e32 v233, v249, v233
	v_mul_f32_e32 v50, v50, v230
	v_mul_f32_e32 v51, v51, v231
	v_mul_f32_e32 v52, v52, v232
	v_mul_f32_e32 v53, v53, v233
	v_cvt_f32_ubyte0_e32 v230, v204
	v_cvt_f32_ubyte1_e32 v231, v204
	v_cvt_f32_ubyte2_e32 v232, v204
	v_cvt_f32_ubyte3_e32 v233, v204
	v_cvt_f32_ubyte0_e32 v242, v208
	v_cvt_f32_ubyte1_e32 v243, v208
	v_cvt_f32_ubyte2_e32 v248, v208
	v_cvt_f32_ubyte3_e32 v249, v208
	v_rcp_iflag_f32_e32 v242, v242
	v_rcp_iflag_f32_e32 v243, v243
	v_rcp_iflag_f32_e32 v248, v248
	v_rcp_iflag_f32_e32 v249, v249
	v_mul_f32_e32 v230, v242, v230
	v_mul_f32_e32 v231, v243, v231
	v_mul_f32_e32 v232, v248, v232
	v_mul_f32_e32 v233, v249, v233
	v_mul_f32_e32 v22, v22, v230
	v_mul_f32_e32 v23, v23, v231
	v_mul_f32_e32 v24, v24, v232
	v_mul_f32_e32 v25, v25, v233
	v_cvt_f32_ubyte0_e32 v230, v205
	v_cvt_f32_ubyte1_e32 v231, v205
	v_cvt_f32_ubyte2_e32 v232, v205
	v_cvt_f32_ubyte3_e32 v233, v205
	v_cvt_f32_ubyte0_e32 v242, v209
	v_cvt_f32_ubyte1_e32 v243, v209
	v_cvt_f32_ubyte2_e32 v248, v209
	v_cvt_f32_ubyte3_e32 v249, v209
	v_rcp_iflag_f32_e32 v242, v242
	v_rcp_iflag_f32_e32 v243, v243
	v_rcp_iflag_f32_e32 v248, v248
	v_rcp_iflag_f32_e32 v249, v249
	v_mul_f32_e32 v230, v242, v230
	v_mul_f32_e32 v231, v243, v231
	v_mul_f32_e32 v232, v248, v232
	v_mul_f32_e32 v233, v249, v233
	v_mul_f32_e32 v18, v18, v230
	v_mul_f32_e32 v19, v19, v231
	v_mul_f32_e32 v20, v20, v232
	v_mul_f32_e32 v21, v21, v233
	s_waitcnt vmcnt(5)
	v_cvt_f32_ubyte0_e32 v230, v210
	v_cvt_f32_ubyte1_e32 v231, v210
	v_cvt_f32_ubyte2_e32 v232, v210
	v_cvt_f32_ubyte3_e32 v233, v210
	v_cvt_f32_ubyte0_e32 v242, v214
	v_cvt_f32_ubyte1_e32 v243, v214
	v_cvt_f32_ubyte2_e32 v248, v214
	v_cvt_f32_ubyte3_e32 v249, v214
	v_rcp_iflag_f32_e32 v242, v242
	v_rcp_iflag_f32_e32 v243, v243
	v_rcp_iflag_f32_e32 v248, v248
	v_rcp_iflag_f32_e32 v249, v249
	v_mul_f32_e32 v230, v242, v230
	v_mul_f32_e32 v231, v243, v231
	v_mul_f32_e32 v232, v248, v232
	v_mul_f32_e32 v233, v249, v233
	v_mul_f32_e32 v46, v46, v230
	v_mul_f32_e32 v47, v47, v231
	v_mul_f32_e32 v48, v48, v232
	v_mul_f32_e32 v49, v49, v233
	v_cvt_f32_ubyte0_e32 v230, v211
	v_cvt_f32_ubyte1_e32 v231, v211
	v_cvt_f32_ubyte2_e32 v232, v211
	v_cvt_f32_ubyte3_e32 v233, v211
	v_cvt_f32_ubyte0_e32 v242, v215
	v_cvt_f32_ubyte1_e32 v243, v215
	v_cvt_f32_ubyte2_e32 v248, v215
	v_cvt_f32_ubyte3_e32 v249, v215
	v_rcp_iflag_f32_e32 v242, v242
	v_rcp_iflag_f32_e32 v243, v243
	v_rcp_iflag_f32_e32 v248, v248
	v_rcp_iflag_f32_e32 v249, v249
	v_mul_f32_e32 v230, v242, v230
	v_mul_f32_e32 v231, v243, v231
	v_mul_f32_e32 v232, v248, v232
	v_mul_f32_e32 v233, v249, v233
	v_mul_f32_e32 v42, v42, v230
	v_mul_f32_e32 v43, v43, v231
	v_mul_f32_e32 v44, v44, v232
	v_mul_f32_e32 v45, v45, v233
	v_cvt_f32_ubyte0_e32 v230, v212
	v_cvt_f32_ubyte1_e32 v231, v212
	v_cvt_f32_ubyte2_e32 v232, v212
	v_cvt_f32_ubyte3_e32 v233, v212
	v_cvt_f32_ubyte0_e32 v242, v220
	v_cvt_f32_ubyte1_e32 v243, v220
	v_cvt_f32_ubyte2_e32 v248, v220
	v_cvt_f32_ubyte3_e32 v249, v220
	v_rcp_iflag_f32_e32 v242, v242
	v_rcp_iflag_f32_e32 v243, v243
	v_rcp_iflag_f32_e32 v248, v248
	v_rcp_iflag_f32_e32 v249, v249
	v_mul_f32_e32 v230, v242, v230
	v_mul_f32_e32 v231, v243, v231
	v_mul_f32_e32 v232, v248, v232
	v_mul_f32_e32 v233, v249, v233
	v_mul_f32_e32 v14, v14, v230
	v_mul_f32_e32 v15, v15, v231
	v_mul_f32_e32 v16, v16, v232
	v_mul_f32_e32 v17, v17, v233
	v_cvt_f32_ubyte0_e32 v230, v213
	v_cvt_f32_ubyte1_e32 v231, v213
	v_cvt_f32_ubyte2_e32 v232, v213
	v_cvt_f32_ubyte3_e32 v233, v213
	v_cvt_f32_ubyte0_e32 v242, v221
	v_cvt_f32_ubyte1_e32 v243, v221
	v_cvt_f32_ubyte2_e32 v248, v221
	v_cvt_f32_ubyte3_e32 v249, v221
	v_rcp_iflag_f32_e32 v242, v242
	v_rcp_iflag_f32_e32 v243, v243
	v_rcp_iflag_f32_e32 v248, v248
	v_rcp_iflag_f32_e32 v249, v249
	v_mul_f32_e32 v230, v242, v230
	v_mul_f32_e32 v231, v243, v231
	v_mul_f32_e32 v232, v248, v232
	v_mul_f32_e32 v233, v249, v233
	v_mul_f32_e32 v10, v10, v230
	v_mul_f32_e32 v11, v11, v231
	v_mul_f32_e32 v12, v12, v232
	v_mul_f32_e32 v13, v13, v233
	s_waitcnt vmcnt(1)
; __device__ __forceinline__ float rcpf(float x) { return __builtin_amdgcn_rcpf(x); }
;     __device__ __forceinline__ bool chain(f32x4 (&acc)[2][2][4][2], const Unit& u, int wr, int wc, int fr, int fq) const {
;     ...
;                 for (int mm = 0; mm < 2; ++mm)
; #pragma unroll
;                     for (int bj = 0; bj < 2; ++bj) { const int m = mp * 2 + mm; const size_t row = (size_t)(row0 + ai * HALF + m * 16); const int c0 = nn * BM + bj * HALF + wc * 32 + 8 * fq; float ga[8], gb[8], o[8];
;                         unpack_u8x8(g0[mm][bj], ga); unpack_u8x8(g1[mm][bj], gb);
; #pragma unroll
;                         for (int n = 0; n < 2; ++n)
; #pragma unroll
;                             for (int j = 0; j < 4; ++j) { const float f = lastb ? ga[n * 4 + j] * (1.f / 255.f) : ga[n * 4 + j] * rcpf(gb[n * 4 + j]); const float v = acc[ai][bj][m][n][j] * f; acc[ai][bj][m][n][j] = v; o[n * 4 + j] = v; }
	v_cvt_f32_ubyte0_e32 v230, v222
	v_cvt_f32_ubyte1_e32 v231, v222
	v_cvt_f32_ubyte2_e32 v232, v222
	v_cvt_f32_ubyte3_e32 v233, v222
	v_cvt_f32_ubyte0_e32 v242, v226
	v_cvt_f32_ubyte1_e32 v243, v226
	v_cvt_f32_ubyte2_e32 v248, v226
	v_cvt_f32_ubyte3_e32 v249, v226
	v_rcp_iflag_f32_e32 v242, v242
	v_rcp_iflag_f32_e32 v243, v243
	v_rcp_iflag_f32_e32 v248, v248
	v_rcp_iflag_f32_e32 v249, v249
	v_mul_f32_e32 v230, v242, v230
	v_mul_f32_e32 v231, v243, v231
	v_mul_f32_e32 v232, v248, v232
	v_mul_f32_e32 v233, v249, v233
	v_mul_f32_e32 v38, v38, v230
	v_mul_f32_e32 v39, v39, v231
	v_mul_f32_e32 v40, v40, v232
	v_mul_f32_e32 v41, v41, v233
	v_cvt_f32_ubyte0_e32 v230, v223
	v_cvt_f32_ubyte1_e32 v231, v223
	v_cvt_f32_ubyte2_e32 v232, v223
	v_cvt_f32_ubyte3_e32 v233, v223
	v_cvt_f32_ubyte0_e32 v242, v227
	v_cvt_f32_ubyte1_e32 v243, v227
	v_cvt_f32_ubyte2_e32 v248, v227
	v_cvt_f32_ubyte3_e32 v249, v227
	v_rcp_iflag_f32_e32 v242, v242
	v_rcp_iflag_f32_e32 v243, v243
	v_rcp_iflag_f32_e32 v248, v248
	v_rcp_iflag_f32_e32 v249, v249
	v_mul_f32_e32 v230, v242, v230
	v_mul_f32_e32 v231, v243, v231
	v_mul_f32_e32 v232, v248, v232
	v_mul_f32_e32 v233, v249, v233
	v_mul_f32_e32 v34, v34, v230
	v_mul_f32_e32 v35, v35, v231
	v_mul_f32_e32 v36, v36, v232
	v_mul_f32_e32 v37, v37, v233
	v_cvt_f32_ubyte0_e32 v230, v224
	v_cvt_f32_ubyte1_e32 v231, v224
	v_cvt_f32_ubyte2_e32 v232, v224
	v_cvt_f32_ubyte3_e32 v233, v224
	v_cvt_f32_ubyte0_e32 v242, v228
	v_cvt_f32_ubyte1_e32 v243, v228
	v_cvt_f32_ubyte2_e32 v248, v228
	v_cvt_f32_ubyte3_e32 v249, v228
	v_rcp_iflag_f32_e32 v242, v242
	v_rcp_iflag_f32_e32 v243, v243
	v_rcp_iflag_f32_e32 v248, v248
	v_rcp_iflag_f32_e32 v249, v249
	v_mul_f32_e32 v230, v242, v230
	v_mul_f32_e32 v231, v243, v231
	v_mul_f32_e32 v232, v248, v232
	v_mul_f32_e32 v233, v249, v233
	v_mul_f32_e32 v6, v6, v230
	v_mul_f32_e32 v7, v7, v231
	v_mul_f32_e32 v8, v8, v232
	v_mul_f32_e32 v9, v9, v233
	v_cvt_f32_ubyte0_e32 v230, v225
	v_cvt_f32_ubyte1_e32 v231, v225
	v_cvt_f32_ubyte2_e32 v232, v225
	v_cvt_f32_ubyte3_e32 v233, v225
	v_cvt_f32_ubyte0_e32 v242, v229
	v_cvt_f32_ubyte1_e32 v243, v229
	v_cvt_f32_ubyte2_e32 v248, v229
	v_cvt_f32_ubyte3_e32 v249, v229
	v_rcp_iflag_f32_e32 v242, v242
	v_rcp_iflag_f32_e32 v243, v243
	v_rcp_iflag_f32_e32 v248, v248
	v_rcp_iflag_f32_e32 v249, v249
	v_mul_f32_e32 v230, v242, v230
	v_mul_f32_e32 v231, v243, v231
	v_mul_f32_e32 v232, v248, v232
	v_mul_f32_e32 v233, v249, v233
	v_mul_f32_e32 v2, v2, v230
	v_mul_f32_e32 v3, v3, v231
	v_mul_f32_e32 v4, v4, v232
	v_mul_f32_e32 v5, v5, v233
	s_waitcnt vmcnt(0)
	s_branch .LBB0_2139
